# grid barrier 4 replaced by a wait on barrier-3 completion plus a scan-done counter (phase 5 does not read moba output); scan workgroups take the small first-round moba items
# speedup vs baseline: 1.0113x; 1.0046x over previous
.LBB0_484:
	v_lshl_add_u64 v[4:5], s[58:59], 0, v[0:1]
	v_add_co_u32_e32 v28, vcc, 0xdcd1000, v4
	v_cvt_pk_bf16_f32 v16, v10, v11
	s_nop 0
	v_addc_co_u32_e32 v29, vcc, 0, v5, vcc
	v_add_co_u32_e32 v30, vcc, 0xdcd9000, v4
	v_cvt_pk_bf16_f32 v17, v12, v13
	s_nop 0
	v_addc_co_u32_e32 v31, vcc, 0, v5, vcc
	v_add_co_u32_e32 v32, vcc, 0xdce1000, v4
	v_cvt_pk_bf16_f32 v18, v14, v15
	v_cvt_pk_bf16_f32 v19, v8, v9
	s_mov_b64 s[12:13], vcc
	v_add_co_u32_e32 v34, vcc, 0xdce9000, v4
	global_load_dwordx4 v[20:23], v[28:29], off
	global_load_dwordx4 v[24:27], v[30:31], off offset:256
	s_mov_b64 s[14:15], vcc
	global_store_dwordx4 v[28:29], v[16:19], off
	v_add_co_u32_e32 v28, vcc, 0xdcf1000, v4
	s_mov_b64 s[6:7], vcc
	v_add_co_u32_e32 v36, vcc, 0xdcf9000, v4
	s_mov_b64 s[8:9], vcc
	v_add_co_u32_e32 v38, vcc, 0xdd01000, v4
	v_lshl_add_u64 v[6:7], s[58:59], 0, v[2:3]
	s_mov_b64 s[10:11], vcc
	v_add_co_u32_e32 v4, vcc, 0xdd09000, v4
	s_mov_b64 s[4:5], vcc
	v_add_co_u32_e32 v6, vcc, s18, v6
	s_add_i32 s20, s20, 8
	s_nop 0
	v_addc_co_u32_e32 v7, vcc, 0, v7, vcc
	global_load_dword v29, v[6:7], off
	v_addc_co_u32_e64 v33, vcc, 0, v5, s[12:13]
	v_addc_co_u32_e64 v35, vcc, 0, v5, s[14:15]
	v_addc_co_u32_e64 v37, vcc, 0, v5, s[8:9]
	v_addc_co_u32_e64 v39, vcc, 0, v5, s[10:11]
	v_lshl_add_u64 v[0:1], v[0:1], 0, s[16:17]
	v_lshl_add_u64 v[2:3], v[2:3], 0, 32
	s_cmp_lt_u32 s20, 56
	s_waitcnt vmcnt(3)
	v_lshlrev_b32_e32 v16, 16, v20
	v_and_b32_e32 v17, 0xffff0000, v20
	v_lshlrev_b32_e32 v18, 16, v21
	v_and_b32_e32 v19, 0xffff0000, v21
	v_lshlrev_b32_e32 v20, 16, v22
	v_and_b32_e32 v21, 0xffff0000, v22
	v_lshlrev_b32_e32 v22, 16, v23
	v_and_b32_e32 v23, 0xffff0000, v23
	s_waitcnt vmcnt(0)
	v_mul_f32_e32 v29, 0x3fb8aa3b, v29
	v_exp_f32_e32 v40, v29
	s_nop 0
	v_pk_fma_f32 v[16:17], v[10:11], v[40:41], v[16:17] op_sel_hi:[1,0,1]
	v_pk_fma_f32 v[18:19], v[12:13], v[40:41], v[18:19] op_sel_hi:[1,0,1]
	v_pk_fma_f32 v[20:21], v[14:15], v[40:41], v[20:21] op_sel_hi:[1,0,1]
	v_pk_fma_f32 v[22:23], v[8:9], v[40:41], v[22:23] op_sel_hi:[1,0,1]
	v_cvt_pk_bf16_f32 v8, v16, v17
	v_cvt_pk_bf16_f32 v9, v18, v19
	v_cvt_pk_bf16_f32 v10, v20, v21
	v_cvt_pk_bf16_f32 v11, v22, v23
	global_store_dwordx4 v[30:31], v[8:11], off offset:256
	global_load_dword v29, v[6:7], off offset:4
	v_lshlrev_b32_e32 v30, 16, v24
	v_and_b32_e32 v31, 0xffff0000, v24
	v_lshlrev_b32_e32 v24, 16, v25
	v_and_b32_e32 v25, 0xffff0000, v25
	v_lshlrev_b32_e32 v40, 16, v26
	v_and_b32_e32 v41, 0xffff0000, v26
	v_lshlrev_b32_e32 v26, 16, v27
	v_and_b32_e32 v27, 0xffff0000, v27
	global_load_dwordx4 v[8:11], v[32:33], off offset:512
	global_load_dwordx4 v[12:15], v[34:35], off offset:768
	s_waitcnt vmcnt(2)
	v_mul_f32_e32 v29, 0x3fb8aa3b, v29
	v_exp_f32_e32 v42, v29
	v_addc_co_u32_e64 v29, vcc, 0, v5, s[6:7]
	v_addc_co_u32_e64 v5, vcc, 0, v5, s[4:5]
	v_pk_fma_f32 v[30:31], v[42:43], v[16:17], v[30:31] op_sel_hi:[0,1,1]
	v_pk_fma_f32 v[24:25], v[42:43], v[18:19], v[24:25] op_sel_hi:[0,1,1]
	v_pk_fma_f32 v[20:21], v[42:43], v[20:21], v[40:41] op_sel_hi:[0,1,1]
	v_pk_fma_f32 v[22:23], v[42:43], v[22:23], v[26:27] op_sel_hi:[0,1,1]
	v_cvt_pk_bf16_f32 v16, v30, v31
	v_cvt_pk_bf16_f32 v17, v24, v25
	v_cvt_pk_bf16_f32 v18, v20, v21
	v_cvt_pk_bf16_f32 v19, v22, v23
	global_store_dwordx4 v[32:33], v[16:19], off offset:512
	global_load_dword v26, v[6:7], off offset:8
	s_waitcnt vmcnt(2)
	v_lshlrev_b32_e32 v32, 16, v14
	v_lshlrev_b32_e32 v16, 16, v8
	v_and_b32_e32 v17, 0xffff0000, v8
	v_lshlrev_b32_e32 v8, 16, v9
	v_and_b32_e32 v9, 0xffff0000, v9
	v_lshlrev_b32_e32 v18, 16, v10
	v_and_b32_e32 v19, 0xffff0000, v10
	v_lshlrev_b32_e32 v10, 16, v11
	v_and_b32_e32 v11, 0xffff0000, v11
	v_and_b32_e32 v33, 0xffff0000, v14
	v_lshlrev_b32_e32 v14, 16, v15
	v_and_b32_e32 v15, 0xffff0000, v15
	s_waitcnt vmcnt(0)
	v_mul_f32_e32 v26, 0x3fb8aa3b, v26
	v_exp_f32_e32 v26, v26
	s_nop 0
	v_pk_fma_f32 v[30:31], v[26:27], v[30:31], v[16:17] op_sel_hi:[0,1,1]
	v_pk_fma_f32 v[24:25], v[26:27], v[24:25], v[8:9] op_sel_hi:[0,1,1]
	v_pk_fma_f32 v[20:21], v[26:27], v[20:21], v[18:19] op_sel_hi:[0,1,1]
	v_pk_fma_f32 v[22:23], v[26:27], v[22:23], v[10:11] op_sel_hi:[0,1,1]
	v_cvt_pk_bf16_f32 v8, v30, v31
	v_cvt_pk_bf16_f32 v9, v24, v25
	v_cvt_pk_bf16_f32 v10, v20, v21
	v_cvt_pk_bf16_f32 v11, v22, v23
	global_store_dwordx4 v[34:35], v[8:11], off offset:768
	global_load_dword v34, v[6:7], off offset:12
	v_lshlrev_b32_e32 v26, 16, v12
	v_and_b32_e32 v27, 0xffff0000, v12
	v_lshlrev_b32_e32 v12, 16, v13
	v_and_b32_e32 v13, 0xffff0000, v13
	global_load_dwordx4 v[8:11], v[28:29], off offset:1024
	global_load_dwordx4 v[16:19], v[36:37], off offset:1280
	s_waitcnt vmcnt(2)
	v_mul_f32_e32 v34, 0x3fb8aa3b, v34
	v_exp_f32_e32 v34, v34
	s_nop 0
	v_pk_fma_f32 v[26:27], v[34:35], v[30:31], v[26:27] op_sel_hi:[0,1,1]
	v_pk_fma_f32 v[24:25], v[34:35], v[24:25], v[12:13] op_sel_hi:[0,1,1]
	v_pk_fma_f32 v[20:21], v[34:35], v[20:21], v[32:33] op_sel_hi:[0,1,1]
	v_pk_fma_f32 v[22:23], v[34:35], v[22:23], v[14:15] op_sel_hi:[0,1,1]
	v_cvt_pk_bf16_f32 v12, v26, v27
	v_cvt_pk_bf16_f32 v13, v24, v25
	v_cvt_pk_bf16_f32 v14, v20, v21
	v_cvt_pk_bf16_f32 v15, v22, v23
	global_store_dwordx4 v[28:29], v[12:15], off offset:1024
	global_load_dword v28, v[6:7], off offset:16
	s_waitcnt vmcnt(2)
	v_lshlrev_b32_e32 v30, 16, v18
	v_lshlrev_b32_e32 v12, 16, v8
	v_and_b32_e32 v13, 0xffff0000, v8
	v_lshlrev_b32_e32 v8, 16, v9
	v_and_b32_e32 v9, 0xffff0000, v9
	v_lshlrev_b32_e32 v14, 16, v10
	v_and_b32_e32 v15, 0xffff0000, v10
	v_lshlrev_b32_e32 v10, 16, v11
	v_and_b32_e32 v11, 0xffff0000, v11
	v_and_b32_e32 v31, 0xffff0000, v18
	v_lshlrev_b32_e32 v18, 16, v19
	v_and_b32_e32 v19, 0xffff0000, v19
	s_waitcnt vmcnt(0)
	v_mul_f32_e32 v28, 0x3fb8aa3b, v28
	v_exp_f32_e32 v28, v28
	s_nop 0
	v_pk_fma_f32 v[26:27], v[28:29], v[26:27], v[12:13] op_sel_hi:[0,1,1]
	v_pk_fma_f32 v[24:25], v[28:29], v[24:25], v[8:9] op_sel_hi:[0,1,1]
	v_pk_fma_f32 v[20:21], v[28:29], v[20:21], v[14:15] op_sel_hi:[0,1,1]
	v_pk_fma_f32 v[22:23], v[28:29], v[22:23], v[10:11] op_sel_hi:[0,1,1]
	v_cvt_pk_bf16_f32 v8, v26, v27
	v_cvt_pk_bf16_f32 v9, v24, v25
	v_cvt_pk_bf16_f32 v10, v20, v21
	v_cvt_pk_bf16_f32 v11, v22, v23
	global_store_dwordx4 v[36:37], v[8:11], off offset:1280
	global_load_dword v32, v[6:7], off offset:20
	v_lshlrev_b32_e32 v28, 16, v16
	v_and_b32_e32 v29, 0xffff0000, v16
	v_lshlrev_b32_e32 v16, 16, v17
	v_and_b32_e32 v17, 0xffff0000, v17
	global_load_dwordx4 v[8:11], v[38:39], off offset:1536
	global_load_dwordx4 v[12:15], v[4:5], off offset:1792
	s_waitcnt vmcnt(2)
	v_mul_f32_e32 v32, 0x3fb8aa3b, v32
	v_exp_f32_e32 v32, v32
	s_nop 0
	v_pk_fma_f32 v[26:27], v[32:33], v[26:27], v[28:29] op_sel_hi:[0,1,1]
	v_pk_fma_f32 v[24:25], v[32:33], v[24:25], v[16:17] op_sel_hi:[0,1,1]
	v_pk_fma_f32 v[20:21], v[32:33], v[20:21], v[30:31] op_sel_hi:[0,1,1]
	v_pk_fma_f32 v[22:23], v[32:33], v[22:23], v[18:19] op_sel_hi:[0,1,1]
	v_cvt_pk_bf16_f32 v16, v26, v27
	v_cvt_pk_bf16_f32 v17, v24, v25
	v_cvt_pk_bf16_f32 v18, v20, v21
	v_cvt_pk_bf16_f32 v19, v22, v23
	global_store_dwordx4 v[38:39], v[16:19], off offset:1536
	global_load_dword v28, v[6:7], off offset:24
	s_waitcnt vmcnt(0)
	v_mul_f32_e32 v28, 0x3fb8aa3b, v28
	v_exp_f32_e32 v28, v28
	v_lshlrev_b32_e32 v16, 16, v8
	v_and_b32_e32 v17, 0xffff0000, v8
	v_lshlrev_b32_e32 v8, 16, v9
	v_and_b32_e32 v9, 0xffff0000, v9
	v_lshlrev_b32_e32 v18, 16, v10
	v_and_b32_e32 v19, 0xffff0000, v10
	v_lshlrev_b32_e32 v10, 16, v11
	v_and_b32_e32 v11, 0xffff0000, v11
	v_pk_fma_f32 v[16:17], v[28:29], v[26:27], v[16:17] op_sel_hi:[0,1,1]
	v_pk_fma_f32 v[24:25], v[28:29], v[24:25], v[8:9] op_sel_hi:[0,1,1]
	v_pk_fma_f32 v[18:19], v[28:29], v[20:21], v[18:19] op_sel_hi:[0,1,1]
	v_pk_fma_f32 v[20:21], v[28:29], v[22:23], v[10:11] op_sel_hi:[0,1,1]
	v_cvt_pk_bf16_f32 v8, v16, v17
	v_cvt_pk_bf16_f32 v9, v24, v25
	v_cvt_pk_bf16_f32 v10, v18, v19
	v_cvt_pk_bf16_f32 v11, v20, v21
	global_store_dwordx4 v[4:5], v[8:11], off offset:1792
	global_load_dword v10, v[6:7], off offset:28
	v_lshlrev_b32_e32 v4, 16, v12
	v_and_b32_e32 v5, 0xffff0000, v12
	v_lshlrev_b32_e32 v6, 16, v13
	v_and_b32_e32 v7, 0xffff0000, v13
	v_lshlrev_b32_e32 v8, 16, v14
	v_and_b32_e32 v9, 0xffff0000, v14
	v_lshlrev_b32_e32 v22, 16, v15
	v_and_b32_e32 v23, 0xffff0000, v15
	s_waitcnt vmcnt(0)
	v_mul_f32_e32 v10, 0x3fb8aa3b, v10
	v_exp_f32_e32 v26, v10
	s_nop 0
	v_pk_fma_f32 v[10:11], v[26:27], v[16:17], v[4:5] op_sel_hi:[0,1,1]
	v_pk_fma_f32 v[12:13], v[26:27], v[24:25], v[6:7] op_sel_hi:[0,1,1]
	v_pk_fma_f32 v[14:15], v[26:27], v[18:19], v[8:9] op_sel_hi:[0,1,1]
	v_pk_fma_f32 v[8:9], v[26:27], v[20:21], v[22:23] op_sel_hi:[0,1,1]
	s_cbranch_scc1 .LBB0_484
	s_add_i32 s19, s19, s42
	s_cmpk_gt_i32 s19, 0x80
	s_cbranch_scc0 .LBB0_483
	s_waitcnt vmcnt(0)
	s_barrier
	s_mov_b64 s[98:99], exec
	v_readlane_b32 s100, v255, 1
	v_readlane_b32 s101, v255, 2
	s_nop 1
	s_mov_b64 exec, s[100:101]
	s_cbranch_execz .Lscan_sig_skip
	buffer_wbl2 sc1
	s_waitcnt vmcnt(0)
	v_readlane_b32 s100, v255, 5
	v_readlane_b32 s101, v255, 6
	v_mov_b32_e32 v217, 0x300
	v_mov_b32_e32 v230, 1
	s_nop 4
	global_atomic_add v217, v230, s[100:101]
.Lscan_sig_skip:
	s_mov_b64 exec, s[98:99]
.LBB0_486:
	v_readlane_b32 s0, v255, 3
	v_readlane_b32 s1, v255, 4
	s_andn2_b64 vcc, exec, s[0:1]
	s_nop 0
	v_cndmask_b32_e64 v0, 0, 1, s[0:1]
	v_cmp_ne_u32_e64 s[38:39], 1, v0
	s_cbranch_vccnz .LBB0_565
	s_not_b32 s2, s76
	s_add_u32 s52, s58, 0x2cd1000
	s_addc_u32 s53, s59, 0
	s_add_u32 s33, s58, 0x8cd1000
	s_addc_u32 s72, s59, 0
	s_add_u32 s73, s58, 0xbd0000
	v_mbcnt_lo_u32_b32 v0, -1, 0
	s_addc_u32 s74, s59, 0
	v_mbcnt_hi_u32_b32 v196, -1, v0
	s_add_u32 s62, s58, 0xcd1000
	v_and_b32_e32 v0, 64, v196
	s_addc_u32 s63, s59, 0
	s_mov_b32 s67, 0
	v_mov_b32_e32 v33, 0
	s_movk_i32 s75, 0xff
	s_movk_i32 s77, 0x1800
	s_mov_b32 s78, 0xefa18f08
	v_xor_b32_e32 v197, 32, v196
	v_add_u32_e32 v198, 64, v0
	v_mov_b32_e32 v199, 0xff800000
	v_mov_b32_e32 v200, 0x3f803f80
	s_mov_b32 s6, 0
	s_mov_b32 s79, 0
	s_branch .LBB0_490

.LBB0_565:
	s_cbranch_execz .LBB0_643
	s_lshl_b32 s0, s76, 2
	s_and_b32 s73, s0, 28
	s_lshl_b32 s0, s76, 11
	s_ashr_i32 s33, s76, 3
	s_sub_i32 s33, 63, s33
	s_and_b32 s52, s0, 0x3000
	s_ashr_i32 s2, s42, 3
	s_not_b32 s72, s33
	s_or_b32 s74, s52, 64
	s_add_u32 s66, s58, 0x2cd1000
	s_addc_u32 s67, s59, 0
	s_add_u32 s75, s58, 0x8cd1000
	s_addc_u32 s77, s59, 0
	s_add_u32 s78, s58, 0xbd0000
	v_mbcnt_lo_u32_b32 v0, -1, 0
	s_addc_u32 s79, s59, 0
	v_mbcnt_hi_u32_b32 v196, -1, v0
	s_mov_b32 s63, 0
	s_add_u32 s68, s58, 0xcd1000
	v_and_b32_e32 v0, 64, v196
	s_mov_b32 s53, s63
	s_addc_u32 s69, s59, 0
	v_mov_b32_e32 v33, 0
	s_movk_i32 s80, 0xff
	s_movk_i32 s81, 0x1800
	s_mov_b32 s82, 0xefa18f08
	v_xor_b32_e32 v197, 32, v196
	v_add_u32_e32 v198, 64, v0
	v_mov_b32_e32 v199, 0xff800000
	v_mov_b32_e32 v200, 0x3f803f80
	s_mov_b32 s6, 0
	s_mov_b32 s83, 0
	v_readlane_b32 s98, v255, 14
	s_nop 3
	s_cmp_lg_u32 s98, 0
	s_cbranch_scc1 .Lmoba_dq_latch2
	s_branch .LBB0_569

.Lb3w_done_c:
	v_mov_b32_e32 v217, 0x300
	v_mov_b32_e32 v230, 0x81
.Lb3w_loop2_c:
	global_load_dword v254, v217, s[100:101] sc1
	s_waitcnt vmcnt(0)
	v_cmp_ge_u32_e32 vcc, v254, v230
	s_cbranch_vccnz .Lb3w_done2_c
	s_sleep 1
	v_add_u32_e32 v231, 1, v231
	v_cmp_gt_u32_e32 vcc, 0x8000, v231
	s_cbranch_vccnz .Lb3w_loop2_c

.LBB0_695:
	s_waitcnt lgkmcnt(0)
	v_mov_b32_e32 v0, v207
	s_barrier
	s_nop 0
	v_ashrrev_i32_e32 v0, 6, v0
	v_lshl_add_u32 v0, s76, 2, v0
	s_nop 0
	v_readfirstlane_b32 s2, v0
	s_cmpk_gt_i32 s2, 0x7ff
	s_cbranch_scc1 .LBB0_724
	s_lshl_b32 s0, s2, 5
	s_lshl_b32 s28, s42, 2
	s_and_b32 s29, s0, 32
	s_add_u32 s4, s58, 0x9cd1000
	s_addc_u32 s5, s59, 0
	s_add_u32 s30, s58, 0xc50000
	s_addc_u32 s31, s59, 0
	s_add_u32 s33, s58, 0xdcd1000
	s_addc_u32 s34, s59, 0
	s_add_u32 s6, s58, 0xccd1000
	v_mbcnt_lo_u32_b32 v0, -1, 0
	s_addc_u32 s7, s59, 0
	s_add_i32 s35, s29, 32
	s_mov_b32 s9, 0
	v_mov_b32_e32 v133, 0
	s_mov_b64 s[10:11], 0x8000
	s_movk_i32 s36, 0x2000
	s_movk_i32 s37, 0x4000
	s_movk_i32 s40, 0x6000
	s_mov_b64 s[12:13], 0xacd1080
	s_mov_b32 s41, 0xbcd1000
	s_mov_b32 s52, 0xbcd2000
	s_mov_b32 s53, 0xbcd3000
	s_mov_b32 s62, 0xbcd4000
	s_add_u32 s98, s58, 0xbcd1000
	s_addc_u32 s99, s59, 0
	s_mov_b64 s[14:15], 0x80
	s_movk_i32 s63, 0x1800
	s_mov_b64 s[16:17], 0x2cd2400
	s_mov_b32 s66, 0x2cd2000
	s_mov_b64 s[18:19], 0xcd1400
	v_mov_b32_e32 v141, 0x3727c5ac
	s_mov_b32 s67, 0x800000
	s_mov_b32 s68, 0xcd1000
	v_mbcnt_hi_u32_b32 v143, -1, v0
	s_branch .LBB0_698
